# retention mixer: decay factor computed as exp2(min(d*lgf, d*(-lgb))) (bit-identical, ~35% fewer VALU ops), QK MFMAs grouped ahead of the VALU block
# speedup vs baseline: 1.0054x; 1.0054x over previous
; #define RT_COMMIT(KR, VR, buf) do { LAS unsigned char* bb_ = lds + (buf) * MX_BUF; \
;         if (kcopy) *(LAS u32x4*)(bb_ + krow * KP + kch * 16) = KR; *(LAS u32x4*)(bb_ + MX_KBYTES + vr * VP + vc * 16) = VR; } while (0)
; __device__ __forceinline__ void wg_ret_task(ParamsCP pp, int layer, LAS unsigned char* lds, int b, int h, int qb, int tid_in) {
;     ...
;     __syncthreads();
;     RT_ISSUE(kr0s, vr0s, 0); RT_COMMIT(kr0s, vr0s, 0); RT_ISSUE(kr1s, vr1s, 1);
;     __syncthreads();
; #pragma unroll 1
;     for (int st = 0; st < 65; st += 2) {
;         RT_ISSUE(kr0s, vr0s, st + 2); RT_COMPUTE(st, 0); RT_COMMIT(kr1s, vr1s, 1); __syncthreads();
.LBB0_408:
	s_or_b64 exec, exec, s[4:5]
	ds_read_b128 v[96:99], v134
	ds_read_b128 v[100:103], v134 offset:64
	v_mov_b32_e32 v0, s15
	v_mov_b32_e32 v2, s14
	v_cndmask_b32_e64 v0, v0, v2, s[10:11]
	s_waitcnt lgkmcnt(1)
	v_mfma_f32_16x16x32_bf16 v[104:107], v[96:99], v[4:7], 0
	v_or_b32_e32 v0, v0, v124
	v_lshl_add_u64 v[2:3], v[0:1], 1, v[118:119]
	ds_read_b128 v[108:111], v134 offset:2304
	ds_read_b128 v[138:141], v134 offset:2368
	v_mfma_f32_16x16x32_bf16 v[96:99], v[96:99], v[12:15], 0
	s_cmpk_lg_i32 s60, 0xf800
	s_cselect_b64 s[4:5], -1, 0
	s_cmpk_eq_i32 s60, 0xf800
	s_waitcnt lgkmcnt(2)
	v_mfma_f32_16x16x32_bf16 v[104:107], v[100:103], v[8:11], v[104:107]
	v_add_u32_e32 v137, s60, v133
	v_mov_b32_e32 v0, 0
	v_mfma_f32_16x16x32_bf16 v[100:103], v[100:103], v[16:19], v[96:99]
	s_nop 2
	global_load_dwordx4 v[96:99], v[2:3], off
	s_waitcnt lgkmcnt(1)
	v_mfma_f32_16x16x32_bf16 v[112:115], v[108:111], v[4:7], 0
	v_mov_b32_e32 v2, 0
	v_mfma_f32_16x16x32_bf16 v[108:111], v[108:111], v[12:15], 0
	s_waitcnt lgkmcnt(0)
	v_mfma_f32_16x16x32_bf16 v[112:115], v[138:141], v[8:11], v[112:115]
	v_mfma_f32_16x16x32_bf16 v[108:111], v[138:141], v[16:19], v[108:111]
	ds_read_b64 v[148:149], v135 offset:8704
	ds_read_b64 v[150:151], v135 offset:8736
	ds_read_b64 v[152:153], v135 offset:9984
	ds_read_b64 v[154:155], v135 offset:10016
	ds_read_b64 v[156:157], v135 offset:11264
	ds_read_b64 v[158:159], v135 offset:11296
	ds_read_b64 v[160:161], v135 offset:12544
	ds_read_b64 v[162:163], v135 offset:12576
	ds_read_b64 v[164:165], v135 offset:13824
	ds_read_b64 v[166:167], v135 offset:13856
	ds_read_b64 v[168:169], v135 offset:15104
	ds_read_b64 v[170:171], v135 offset:15136
	ds_read_b64 v[172:173], v135 offset:16384
	ds_read_b64 v[174:175], v135 offset:16416
	v_add_u32_e32 v136, s60, v131
	v_cvt_f32_i32_e32 v180, v137
	v_cvt_f32_i32_e32 v181, v136
	v_mov_b32_e32 v200, v180
	v_add_f32_e32 v201, 0xbf800000, v180
	v_add_f32_e32 v202, 0xc0000000, v180
	v_add_f32_e32 v203, 0xc0400000, v180
	v_mul_f32_e32 v208, v126, v200
	v_mul_f32_e32 v209, v126, v201
	v_mul_f32_e32 v210, v126, v202
	v_mul_f32_e32 v211, v126, v203
	v_mul_f32_e64 v212, v200, -v127
	v_mul_f32_e64 v213, v201, -v127
	v_mul_f32_e64 v214, v202, -v127
	v_mul_f32_e64 v215, v203, -v127
	v_min_f32_e32 v208, v208, v212
	v_min_f32_e32 v209, v209, v213
	v_min_f32_e32 v210, v210, v214
	v_min_f32_e32 v211, v211, v215
	v_exp_f32_e32 v208, v208
	v_exp_f32_e32 v209, v209
	v_exp_f32_e32 v210, v210
	v_exp_f32_e32 v211, v211
	v_mul_f32_e32 v184, v208, v104
	v_mul_f32_e32 v185, v209, v105
	v_mul_f32_e32 v186, v210, v106
	v_mul_f32_e32 v187, v211, v107
	v_add_f32_e32 v200, 0xc1800000, v180
	v_add_f32_e32 v201, 0xc1880000, v180
	v_add_f32_e32 v202, 0xc1900000, v180
	v_add_f32_e32 v203, 0xc1980000, v180
	v_mul_f32_e32 v208, v126, v200
	v_mul_f32_e32 v209, v126, v201
	v_mul_f32_e32 v210, v126, v202
	v_mul_f32_e32 v211, v126, v203
	v_mul_f32_e64 v212, v200, -v127
	v_mul_f32_e64 v213, v201, -v127
	v_mul_f32_e64 v214, v202, -v127
	v_mul_f32_e64 v215, v203, -v127
	v_min_f32_e32 v208, v208, v212
	v_min_f32_e32 v209, v209, v213
	v_min_f32_e32 v210, v210, v214
	v_min_f32_e32 v211, v211, v215
	v_exp_f32_e32 v208, v208
	v_exp_f32_e32 v209, v209
	v_exp_f32_e32 v210, v210
	v_exp_f32_e32 v211, v211
	v_mul_f32_e32 v188, v208, v112
	v_mul_f32_e32 v189, v209, v113
	v_mul_f32_e32 v190, v210, v114
	v_mul_f32_e32 v191, v211, v115
	v_cndmask_b32_e64 v188, 0, v188, s[4:5]
	v_cndmask_b32_e64 v189, 0, v189, s[4:5]
	v_cndmask_b32_e64 v190, 0, v190, s[4:5]
	v_cndmask_b32_e64 v191, 0, v191, s[4:5]
	v_mov_b32_e32 v200, v181
	v_add_f32_e32 v201, 0xbf800000, v181
	v_add_f32_e32 v202, 0xc0000000, v181
	v_add_f32_e32 v203, 0xc0400000, v181
	v_mul_f32_e32 v208, v126, v200
	v_mul_f32_e32 v209, v126, v201
	v_mul_f32_e32 v210, v126, v202
	v_mul_f32_e32 v211, v126, v203
	v_mul_f32_e64 v212, v200, -v127
	v_mul_f32_e64 v213, v201, -v127
	v_mul_f32_e64 v214, v202, -v127
	v_mul_f32_e64 v215, v203, -v127
	v_min_f32_e32 v208, v208, v212
	v_min_f32_e32 v209, v209, v213
	v_min_f32_e32 v210, v210, v214
	v_min_f32_e32 v211, v211, v215
	v_exp_f32_e32 v208, v208
	v_exp_f32_e32 v209, v209
	v_exp_f32_e32 v210, v210
	v_exp_f32_e32 v211, v211
	v_mul_f32_e32 v192, v208, v100
	v_mul_f32_e32 v193, v209, v101
	v_mul_f32_e32 v194, v210, v102
	v_mul_f32_e32 v195, v211, v103
	v_add_f32_e32 v200, 0xc1800000, v181
	v_add_f32_e32 v201, 0xc1880000, v181
	v_add_f32_e32 v202, 0xc1900000, v181
	v_add_f32_e32 v203, 0xc1980000, v181
	v_mul_f32_e32 v208, v126, v200
	v_mul_f32_e32 v209, v126, v201
	v_mul_f32_e32 v210, v126, v202
	v_mul_f32_e32 v211, v126, v203
	v_mul_f32_e64 v212, v200, -v127
	v_mul_f32_e64 v213, v201, -v127
	v_mul_f32_e64 v214, v202, -v127
	v_mul_f32_e64 v215, v203, -v127
	v_min_f32_e32 v208, v208, v212
	v_min_f32_e32 v209, v209, v213
	v_min_f32_e32 v210, v210, v214
	v_min_f32_e32 v211, v211, v215
	v_exp_f32_e32 v208, v208
	v_exp_f32_e32 v209, v209
	v_exp_f32_e32 v210, v210
	v_exp_f32_e32 v211, v211
	v_mul_f32_e32 v196, v208, v108
	v_mul_f32_e32 v197, v209, v109
	v_mul_f32_e32 v198, v210, v110
	v_mul_f32_e32 v199, v211, v111
	v_cndmask_b32_e64 v196, 0, v196, s[4:5]
	v_cndmask_b32_e64 v197, 0, v197, s[4:5]
	v_cndmask_b32_e64 v198, 0, v198, s[4:5]
	v_cndmask_b32_e64 v199, 0, v199, s[4:5]
	v_cvt_pk_bf16_f32 v102, v184, v185
	v_cvt_pk_bf16_f32 v103, v186, v187
	v_cvt_pk_bf16_f32 v104, v188, v189
	v_cvt_pk_bf16_f32 v105, v190, v191
	v_cvt_pk_bf16_f32 v106, v192, v193
	v_cvt_pk_bf16_f32 v107, v194, v195
	v_cvt_pk_bf16_f32 v108, v196, v197
	v_cvt_pk_bf16_f32 v109, v198, v199
	ds_read_b64 v[176:177], v135 offset:17664
	ds_read_b64 v[178:179], v135 offset:17696
	s_waitcnt lgkmcnt(2)
	v_mfma_f32_16x16x32_bf16 v[72:75], v[102:105], v[148:151], v[72:75]
	v_mfma_f32_16x16x32_bf16 v[56:59], v[106:109], v[148:151], v[56:59]
	v_mfma_f32_16x16x32_bf16 v[88:91], v[102:105], v[152:155], v[88:91]
	v_mfma_f32_16x16x32_bf16 v[52:55], v[106:109], v[152:155], v[52:55]
	v_mfma_f32_16x16x32_bf16 v[84:87], v[102:105], v[156:159], v[84:87]
	v_mfma_f32_16x16x32_bf16 v[48:51], v[106:109], v[156:159], v[48:51]
	v_mfma_f32_16x16x32_bf16 v[80:83], v[102:105], v[160:163], v[80:83]
	v_mfma_f32_16x16x32_bf16 v[44:47], v[106:109], v[160:163], v[44:47]
	v_mfma_f32_16x16x32_bf16 v[76:79], v[102:105], v[164:167], v[76:79]
	v_mfma_f32_16x16x32_bf16 v[40:43], v[106:109], v[164:167], v[40:43]
	v_mfma_f32_16x16x32_bf16 v[68:71], v[102:105], v[168:171], v[68:71]
	v_mfma_f32_16x16x32_bf16 v[36:39], v[106:109], v[168:171], v[36:39]
	v_mfma_f32_16x16x32_bf16 v[64:67], v[102:105], v[172:175], v[64:67]
	v_mfma_f32_16x16x32_bf16 v[32:35], v[106:109], v[172:175], v[32:35]
	s_waitcnt lgkmcnt(0)
	v_mfma_f32_16x16x32_bf16 v[60:63], v[102:105], v[176:179], v[60:63]
	v_mfma_f32_16x16x32_bf16 v[28:31], v[106:109], v[176:179], v[28:31]
	s_and_saveexec_b64 s[4:5], s[8:9]
	s_cbranch_execz .LBB0_424
	v_add_u32_e32 v0, v129, v116
	s_waitcnt vmcnt(2)
	ds_write_b128 v0, v[24:27] offset:29184

; #define RT_COMMIT(KR, VR, buf) do { LAS unsigned char* bb_ = lds + (buf) * MX_BUF; \
;         if (kcopy) *(LAS u32x4*)(bb_ + krow * KP + kch * 16) = KR; *(LAS u32x4*)(bb_ + MX_KBYTES + vr * VP + vc * 16) = VR; } while (0)
; __device__ __forceinline__ void wg_ret_task(ParamsCP pp, int layer, LAS unsigned char* lds, int b, int h, int qb, int tid_in) {
;     ...
;     __syncthreads();
;     RT_ISSUE(kr0s, vr0s, 0); RT_COMMIT(kr0s, vr0s, 0); RT_ISSUE(kr1s, vr1s, 1);
;     __syncthreads();
; #pragma unroll 1
;     for (int st = 0; st < 65; st += 2) {
;         RT_ISSUE(kr0s, vr0s, st + 2); RT_COMPUTE(st, 0); RT_COMMIT(kr1s, vr1s, 1); __syncthreads();
;         if (st + 1 < 65) { RT_ISSUE(kr1s, vr1s, st + 3); RT_COMPUTE(st + 1, 1); RT_COMMIT(kr0s, vr0s, 0); __syncthreads(); }
.LBB0_427:
	s_or_b64 exec, exec, s[4:5]
	v_mov_b32_e32 v0, s15
	v_mov_b32_e32 v2, s14
	v_cndmask_b32_e64 v0, v0, v2, s[10:11]
	v_or_b32_e32 v0, v0, v124
	v_lshl_add_u64 v[2:3], v[0:1], 1, v[118:119]
	global_load_dwordx4 v[92:95], v[2:3], off
	ds_read_b128 v[100:103], v134 offset:29184
	ds_read_b128 v[138:141], v134 offset:31488
	ds_read_b128 v[104:107], v134 offset:29248
	ds_read_b128 v[142:145], v134 offset:31552
	s_waitcnt lgkmcnt(3)
	v_mfma_f32_16x16x32_bf16 v[108:111], v[100:103], v[4:7], 0
	v_mfma_f32_16x16x32_bf16 v[100:103], v[100:103], v[12:15], 0
	s_waitcnt lgkmcnt(1)
	v_mfma_f32_16x16x32_bf16 v[112:115], v[104:107], v[8:11], v[108:111]
	v_mfma_f32_16x16x32_bf16 v[108:111], v[138:141], v[4:7], 0
	v_mfma_f32_16x16x32_bf16 v[104:107], v[104:107], v[16:19], v[100:103]
	v_mfma_f32_16x16x32_bf16 v[100:103], v[138:141], v[12:15], 0
	s_waitcnt lgkmcnt(0)
	v_mfma_f32_16x16x32_bf16 v[108:111], v[142:145], v[8:11], v[108:111]
	v_mfma_f32_16x16x32_bf16 v[100:103], v[142:145], v[16:19], v[100:103]
	ds_read_b64 v[148:149], v135 offset:37888
	ds_read_b64 v[150:151], v135 offset:37920
	ds_read_b64 v[152:153], v135 offset:39168
	ds_read_b64 v[154:155], v135 offset:39200
	ds_read_b64 v[156:157], v135 offset:40448
	ds_read_b64 v[158:159], v135 offset:40480
	ds_read_b64 v[160:161], v135 offset:41728
	ds_read_b64 v[162:163], v135 offset:41760
	ds_read_b64 v[164:165], v135 offset:43008
	ds_read_b64 v[166:167], v135 offset:43040
	ds_read_b64 v[168:169], v135 offset:44288
	ds_read_b64 v[170:171], v135 offset:44320
	ds_read_b64 v[172:173], v135 offset:45568
	ds_read_b64 v[174:175], v135 offset:45600
	v_cvt_f32_i32_e32 v180, v137
	v_cvt_f32_i32_e32 v181, v136
	v_add_f32_e32 v200, 0xc2000000, v180
	v_add_f32_e32 v201, 0xc2040000, v180
	v_add_f32_e32 v202, 0xc2080000, v180
	v_add_f32_e32 v203, 0xc20c0000, v180
	v_mul_f32_e32 v208, v126, v200
	v_mul_f32_e32 v209, v126, v201
	v_mul_f32_e32 v210, v126, v202
	v_mul_f32_e32 v211, v126, v203
	v_mul_f32_e64 v212, v200, -v127
	v_mul_f32_e64 v213, v201, -v127
	v_mul_f32_e64 v214, v202, -v127
	v_mul_f32_e64 v215, v203, -v127
	v_min_f32_e32 v208, v208, v212
	v_min_f32_e32 v209, v209, v213
	v_min_f32_e32 v210, v210, v214
	v_min_f32_e32 v211, v211, v215
	v_exp_f32_e32 v208, v208
	v_exp_f32_e32 v209, v209
	v_exp_f32_e32 v210, v210
	v_exp_f32_e32 v211, v211
	v_mul_f32_e32 v184, v208, v112
	v_mul_f32_e32 v185, v209, v113
	v_mul_f32_e32 v186, v210, v114
	v_mul_f32_e32 v187, v211, v115
	v_add_f32_e32 v200, 0xc2400000, v180
	v_add_f32_e32 v201, 0xc2440000, v180
	v_add_f32_e32 v202, 0xc2480000, v180
	v_add_f32_e32 v203, 0xc24c0000, v180
	v_mul_f32_e32 v208, v126, v200
	v_mul_f32_e32 v209, v126, v201
	v_mul_f32_e32 v210, v126, v202
	v_mul_f32_e32 v211, v126, v203
	v_mul_f32_e64 v212, v200, -v127
	v_mul_f32_e64 v213, v201, -v127
	v_mul_f32_e64 v214, v202, -v127
	v_mul_f32_e64 v215, v203, -v127
	v_min_f32_e32 v208, v208, v212
	v_min_f32_e32 v209, v209, v213
	v_min_f32_e32 v210, v210, v214
	v_min_f32_e32 v211, v211, v215
	v_exp_f32_e32 v208, v208
	v_exp_f32_e32 v209, v209
	v_exp_f32_e32 v210, v210
	v_exp_f32_e32 v211, v211
	v_mul_f32_e32 v188, v208, v108
	v_mul_f32_e32 v189, v209, v109
	v_mul_f32_e32 v190, v210, v110
	v_mul_f32_e32 v191, v211, v111
	v_add_f32_e32 v200, 0xc2000000, v181
	v_add_f32_e32 v201, 0xc2040000, v181
	v_add_f32_e32 v202, 0xc2080000, v181
	v_add_f32_e32 v203, 0xc20c0000, v181
	v_mul_f32_e32 v208, v126, v200
	v_mul_f32_e32 v209, v126, v201
	v_mul_f32_e32 v210, v126, v202
	v_mul_f32_e32 v211, v126, v203
	v_mul_f32_e64 v212, v200, -v127
	v_mul_f32_e64 v213, v201, -v127
	v_mul_f32_e64 v214, v202, -v127
	v_mul_f32_e64 v215, v203, -v127
	v_min_f32_e32 v208, v208, v212
	v_min_f32_e32 v209, v209, v213
	v_min_f32_e32 v210, v210, v214
	v_min_f32_e32 v211, v211, v215
	v_exp_f32_e32 v208, v208
	v_exp_f32_e32 v209, v209
	v_exp_f32_e32 v210, v210
	v_exp_f32_e32 v211, v211
	v_mul_f32_e32 v192, v208, v104
	v_mul_f32_e32 v193, v209, v105
	v_mul_f32_e32 v194, v210, v106
	v_mul_f32_e32 v195, v211, v107
	v_add_f32_e32 v200, 0xc2400000, v181
	v_add_f32_e32 v201, 0xc2440000, v181
	v_add_f32_e32 v202, 0xc2480000, v181
	v_add_f32_e32 v203, 0xc24c0000, v181
	v_mul_f32_e32 v208, v126, v200
	v_mul_f32_e32 v209, v126, v201
	v_mul_f32_e32 v210, v126, v202
	v_mul_f32_e32 v211, v126, v203
	v_mul_f32_e64 v212, v200, -v127
	v_mul_f32_e64 v213, v201, -v127
	v_mul_f32_e64 v214, v202, -v127
	v_mul_f32_e64 v215, v203, -v127
	v_min_f32_e32 v208, v208, v212
	v_min_f32_e32 v209, v209, v213
	v_min_f32_e32 v210, v210, v214
	v_min_f32_e32 v211, v211, v215
	v_exp_f32_e32 v208, v208
	v_exp_f32_e32 v209, v209
	v_exp_f32_e32 v210, v210
	v_exp_f32_e32 v211, v211
	v_mul_f32_e32 v196, v208, v100
	v_mul_f32_e32 v197, v209, v101
	v_mul_f32_e32 v198, v210, v102
	v_mul_f32_e32 v199, v211, v103
	v_cvt_pk_bf16_f32 v106, v184, v185
	v_cvt_pk_bf16_f32 v107, v186, v187
	v_cvt_pk_bf16_f32 v108, v188, v189
	v_cvt_pk_bf16_f32 v109, v190, v191
	v_cvt_pk_bf16_f32 v102, v192, v193
	v_cvt_pk_bf16_f32 v103, v194, v195
	v_cvt_pk_bf16_f32 v104, v196, v197
	v_cvt_pk_bf16_f32 v105, v198, v199
	ds_read_b64 v[176:177], v135 offset:46848
	ds_read_b64 v[178:179], v135 offset:46880
	s_waitcnt lgkmcnt(2)
	v_mfma_f32_16x16x32_bf16 v[72:75], v[106:109], v[148:151], v[72:75]
	v_mfma_f32_16x16x32_bf16 v[56:59], v[102:105], v[148:151], v[56:59]
	v_mfma_f32_16x16x32_bf16 v[88:91], v[106:109], v[152:155], v[88:91]
	v_mfma_f32_16x16x32_bf16 v[52:55], v[102:105], v[152:155], v[52:55]
	v_mfma_f32_16x16x32_bf16 v[84:87], v[106:109], v[156:159], v[84:87]
	v_mfma_f32_16x16x32_bf16 v[48:51], v[102:105], v[156:159], v[48:51]
	v_mfma_f32_16x16x32_bf16 v[80:83], v[106:109], v[160:163], v[80:83]
	v_mfma_f32_16x16x32_bf16 v[44:47], v[102:105], v[160:163], v[44:47]
	v_mfma_f32_16x16x32_bf16 v[76:79], v[106:109], v[164:167], v[76:79]
	v_mfma_f32_16x16x32_bf16 v[40:43], v[102:105], v[164:167], v[40:43]
	v_mfma_f32_16x16x32_bf16 v[68:71], v[106:109], v[168:171], v[68:71]
	v_mfma_f32_16x16x32_bf16 v[36:39], v[102:105], v[168:171], v[36:39]
	v_mfma_f32_16x16x32_bf16 v[64:67], v[106:109], v[172:175], v[64:67]
	v_mfma_f32_16x16x32_bf16 v[32:35], v[102:105], v[172:175], v[32:35]
	s_waitcnt lgkmcnt(0)
	v_mfma_f32_16x16x32_bf16 v[60:63], v[106:109], v[176:179], v[60:63]
	v_mfma_f32_16x16x32_bf16 v[28:31], v[102:105], v[176:179], v[28:31]
	s_and_saveexec_b64 s[4:5], s[8:9]
	s_cbranch_execz .LBB0_404
	v_add_u32_e32 v0, v129, v116
	ds_write_b128 v0, v[20:23]
	s_branch .LBB0_404
